# stackB + SWA peeled last chunk: same LDS read batching (sub-tiles 0..2)
# baseline (speedup 1.0000x reference)
; #define LAS __attribute__((address_space(3)))
; template <int HD, int DV, int HW, int MODE> ...
;     ...
;     for (int c = 0; c < NC; ++c) {
;         const int jc = i0 - HW + CR * c;
;         __syncthreads();
; #pragma unroll
;         for (int i = 0; i < KLD; ++i) { const int idx = tid + 512 * i, row = idx / KCH, ch = idx % KCH; *(LAS u32x4*)(Kl + row * RSK + ch * 16) = kreg[i]; }
; #pragma unroll
;         for (int i = 0; i < VLD; ++i) { const int idx = tid + 512 * i, row = idx / VCH, ch = idx % VCH; *(LAS u32x4*)(Vl + row * RSV + ch * 16) = vreg[i]; }
;         __syncthreads();
;         if (c + 1 < NC) prefetch(c + 1);
; #pragma unroll
;         for (int u = 0; u < CR / 32; ++u) {
;             const int js = jc + 32 * u;
;             if (js + 31 < iw - HW || js > iw + 31 + HW || js + 31 < 0 || js >= L) continue;
;             f32x16 S;
; #pragma unroll
;             for (int i = 0; i < 16; ++i) S[i] = 0.f;
; #pragma unroll
;             for (int ks = 0; ks < KS; ++ks) { const bf16x8 kf = *(const LAS bf16x8*)(kread + (32 * u) * RSK + 32 * ks); S = __builtin_amdgcn_mfma_f32_32x32x16_bf16(kf, qf[ks], S, 0, 0, 0); }
;             const bool full = (js >= iw + 31 - HW) && (js + 31 <= iw + HW) && js >= 0 && js + 31 < L;
.LBB0_210:
	s_add_i32 s4, s48, 0x100
	s_add_i32 s2, s48, 0x11f
	s_cmp_lt_i32 s2, s53
	s_cselect_b64 s[10:11], -1, 0
	s_cmp_gt_i32 s4, s52
	s_cselect_b64 s[22:23], -1, 0
	s_or_b64 s[10:11], s[10:11], s[22:23]
	s_cmpk_gt_u32 s2, 0x201e
	s_cselect_b64 s[22:23], -1, 0
	s_or_b64 s[10:11], s[22:23], s[10:11]
	v_add_u32_e32 v107, 0x80, v104
	v_add_u32_e32 v106, 0x7e, v104
	v_add_u32_e32 v15, 0x7d, v104
	v_add_u32_e32 v14, 0x7c, v104
	v_add_u32_e32 v13, 0x7b, v104
	v_add_u32_e32 v12, 0x7a, v104
	v_add_u32_e32 v11, 0x79, v104
	v_add_u32_e32 v10, 0x70, v104
	v_add_u32_e32 v9, 0x6f, v104
	v_add_u32_e32 v8, 0x6e, v104
	v_add_u32_e32 v7, 0x6d, v104
	v_add_u32_e32 v6, 0x6c, v104
	v_add_u32_e32 v5, 0x6b, v104
	v_add_u32_e32 v4, 0x6a, v104
	v_add_u32_e32 v3, 0x69, v104
	s_barrier
	s_waitcnt vmcnt(0)
	ds_write_b128 v1, v[84:87]
	ds_write_b128 v2, v[80:83]
	ds_write_b128 v118, v[88:91] offset:18432
	ds_write_b128 v119, v[92:95] offset:18432
	s_and_b64 vcc, exec, s[10:11]
	v_add_u32_e32 v1, v117, v102
	s_waitcnt lgkmcnt(0)
	s_barrier
	s_cbranch_vccnz .LBB0_218
	ds_read_b128 v[48:51], v1
	ds_read_b128 v[80:83], v1 offset:32
	ds_read_b128 v[126:129], v1 offset:64
	ds_read_b128 v[130:133], v1 offset:96
	s_cmp_lt_i32 s4, s49
	s_cselect_b64 s[26:27], -1, 0
	s_and_b64 vcc, exec, s[26:27]
	s_waitcnt lgkmcnt(3)
	v_mfma_f32_32x32x16_bf16 v[48:63], v[48:51], v[76:79], 0
	s_waitcnt lgkmcnt(2)
	v_mfma_f32_32x32x16_bf16 v[48:63], v[80:83], v[72:75], v[48:63]
	s_waitcnt lgkmcnt(1)
	v_mfma_f32_32x32x16_bf16 v[48:63], v[126:129], v[68:71], v[48:63]
	s_waitcnt lgkmcnt(0)
	v_mfma_f32_32x32x16_bf16 v[48:63], v[130:133], v[64:67], v[48:63]
	v_add_u32_e32 v154, v103, v105
	ds_read_b64_tr_b16 v[138:139], v154 offset:18432
	ds_read_b64_tr_b16 v[140:141], v154 offset:19200
	ds_read_b64_tr_b16 v[142:143], v154 offset:21504
	ds_read_b64_tr_b16 v[144:145], v154 offset:22272
	ds_read_b64_tr_b16 v[146:147], v154 offset:18496
	ds_read_b64_tr_b16 v[148:149], v154 offset:19264
	ds_read_b64_tr_b16 v[150:151], v154 offset:21568
	ds_read_b64_tr_b16 v[152:153], v154 offset:22336
	s_cbranch_vccnz .LBB0_213
	s_cmp_gt_i32 s4, s47
	s_cselect_b64 s[10:11], -1, 0
	s_cmpk_gt_u32 s48, 0x1ee0
	s_cselect_b64 s[22:23], -1, 0
	s_or_b64 s[26:27], s[10:11], s[22:23]

; #define LAS __attribute__((address_space(3)))
; __device__ __forceinline__ float xmax32(float v) { const auto r = __builtin_amdgcn_permlane32_swap(__float_as_uint(v), __float_as_uint(v), false, false); return __builtin_fmaxf(__uint_as_float(r[0]), __uint_as_float(r[1])); }
; template <int HD, int DV, int HW, int MODE> ...
;     ...
;             const int js = jc + 32 * u;
;             if (js + 31 < iw - HW || js > iw + 31 + HW || js + 31 < 0 || js >= L) continue;
;             f32x16 S;
; #pragma unroll
;             for (int i = 0; i < 16; ++i) S[i] = 0.f;
; #pragma unroll
;             for (int ks = 0; ks < KS; ++ks) { const bf16x8 kf = *(const LAS bf16x8*)(kread + (32 * u) * RSK + 32 * ks); S = __builtin_amdgcn_mfma_f32_32x32x16_bf16(kf, qf[ks], S, 0, 0, 0); }
;             const bool full = (js >= iw + 31 - HW) && (js + 31 <= iw + HW) && js >= 0 && js + 31 < L;
;             if (!full) {
;                 const int qi = iw + ql;
; #pragma unroll
;                 for (int i = 0; i < 16; ++i) { const int j = js + (i & 7) + 8 * hh + 16 * (i >> 3); const int d = qi - j; const bool ok = (d <= HW) && (d >= -HW) && (j >= 0) && (j < L); S[i] = ok ? S[i] : -INFINITY; }
;             }
;             float mt = xmax32(max16(S));
;             if (__any(mt > m + 8.0f)) {
;                 const float mn = fmaxf(m, mt), a = __builtin_amdgcn_exp2f(m - mn); l *= a; m = mn;
; #pragma unroll
;                 for (int t = 0; t < NTV; ++t) O[t] = O[t] * a;
;             }
; #pragma unroll
;             for (int i = 0; i < 16; ++i) S[i] = __builtin_amdgcn_exp2f(S[i] - m);
;             l += sum16(S);
;             const bf16x8 P0 = pack8(S, 0), P1 = pack8(S, 8);
; #pragma unroll
;             for (int t = 0; t < NTV; ++t) {
;                 const LAS unsigned char* vb = vread + (32 * u) * RSV + 64 * t;
;                 const bf16x8 v0 = tr_pair(vb, vb + 4 * RSV), v1 = tr_pair(vb + 16 * RSV, vb + 20 * RSV);
;                 O[t] = __builtin_amdgcn_mfma_f32_32x32x16_bf16(v0, P0, O[t], 0, 0, 0);
;                 O[t] = __builtin_amdgcn_mfma_f32_32x32x16_bf16(v1, P1, O[t], 0, 0, 0);
;             }
.LBB0_217:
	v_sub_f32_e32 v2, v48, v115
	v_exp_f32_e32 v80, v2
	v_sub_f32_e32 v2, v49, v115
	v_exp_f32_e32 v82, v2
	v_sub_f32_e32 v2, v50, v115
	v_exp_f32_e32 v84, v2
	v_sub_f32_e32 v2, v51, v115
	v_exp_f32_e32 v86, v2
	v_sub_f32_e32 v2, v52, v115
	v_exp_f32_e32 v88, v2
	v_sub_f32_e32 v2, v53, v115
	v_exp_f32_e32 v90, v2
	v_sub_f32_e32 v2, v54, v115
	v_exp_f32_e32 v54, v2
	v_sub_f32_e32 v2, v55, v115
	v_exp_f32_e32 v92, v2
	v_sub_f32_e32 v2, v56, v115
	v_exp_f32_e32 v81, v2
	v_sub_f32_e32 v2, v57, v115
	v_exp_f32_e32 v83, v2
	v_sub_f32_e32 v2, v58, v115
	v_exp_f32_e32 v85, v2
	v_sub_f32_e32 v2, v59, v115
	v_exp_f32_e32 v87, v2
	v_sub_f32_e32 v2, v60, v115
	v_exp_f32_e32 v89, v2
	v_sub_f32_e32 v2, v61, v115
	v_exp_f32_e32 v91, v2
	v_sub_f32_e32 v2, v62, v115
	v_exp_f32_e32 v55, v2
	v_sub_f32_e32 v2, v63, v115
	v_exp_f32_e32 v93, v2
	v_pk_add_f32 v[48:49], v[80:81], v[82:83]
	v_pk_add_f32 v[50:51], v[84:85], v[86:87]
	v_pk_add_f32 v[52:53], v[54:55], v[92:93]
	v_pk_add_f32 v[48:49], v[48:49], v[50:51]
	v_pk_add_f32 v[50:51], v[88:89], v[90:91]
	v_cvt_pk_bf16_f32 v55, v55, v93
	v_pk_add_f32 v[50:51], v[50:51], v[52:53]
	v_cvt_pk_bf16_f32 v52, v81, v83
	v_pk_add_f32 v[48:49], v[48:49], v[50:51]
	v_cvt_pk_bf16_f32 v50, v88, v90
	v_add_f32_e32 v2, v48, v49
	v_cvt_pk_bf16_f32 v48, v80, v82
	v_add_u32_e32 v80, v103, v105
	v_cvt_pk_bf16_f32 v49, v84, v86
	v_cvt_pk_bf16_f32 v51, v54, v92
	v_cvt_pk_bf16_f32 v53, v85, v87
	v_cvt_pk_bf16_f32 v54, v89, v91
	s_waitcnt lgkmcnt(6)
	v_mfma_f32_32x32x16_bf16 v[32:47], v[138:141], v[48:51], v[32:47]
	v_add_f32_e32 v101, v101, v2
	s_waitcnt lgkmcnt(4)
	v_mfma_f32_32x32x16_bf16 v[32:47], v[142:145], v[52:55], v[32:47]
	s_waitcnt lgkmcnt(2)
	v_mfma_f32_32x32x16_bf16 v[16:31], v[146:149], v[48:51], v[16:31]
	s_waitcnt lgkmcnt(0)
	v_mfma_f32_32x32x16_bf16 v[16:31], v[150:153], v[52:55], v[16:31]
.LBB0_218:
	s_or_b32 s5, s4, 32
	s_or_b32 s2, s4, 63
	s_cmp_lt_i32 s2, s53
	s_cselect_b64 s[10:11], -1, 0
	s_cmp_gt_i32 s5, s52
	s_cselect_b64 s[22:23], -1, 0
	s_or_b64 s[10:11], s[10:11], s[22:23]
	s_cmpk_gt_u32 s2, 0x201e
	s_cselect_b64 s[22:23], -1, 0
	s_or_b64 s[10:11], s[22:23], s[10:11]
	s_and_b64 vcc, exec, s[10:11]
	s_cbranch_vccnz .LBB0_226
	ds_read_b128 v[48:51], v1 offset:4608
	ds_read_b128 v[80:83], v1 offset:4640
	ds_read_b128 v[126:129], v1 offset:4672
	ds_read_b128 v[130:133], v1 offset:4704
	s_cmp_lt_i32 s5, s49
	s_cselect_b64 s[26:27], -1, 0
	s_and_b64 vcc, exec, s[26:27]
	s_waitcnt lgkmcnt(3)
	v_mfma_f32_32x32x16_bf16 v[48:63], v[48:51], v[76:79], 0
	s_waitcnt lgkmcnt(2)
	v_mfma_f32_32x32x16_bf16 v[48:63], v[80:83], v[72:75], v[48:63]
	s_waitcnt lgkmcnt(1)
	v_mfma_f32_32x32x16_bf16 v[48:63], v[126:129], v[68:71], v[48:63]
	s_waitcnt lgkmcnt(0)
	v_mfma_f32_32x32x16_bf16 v[48:63], v[130:133], v[64:67], v[48:63]
	v_add_u32_e32 v154, v103, v105
	ds_read_b64_tr_b16 v[138:139], v154 offset:24576
	ds_read_b64_tr_b16 v[140:141], v154 offset:25344
	ds_read_b64_tr_b16 v[142:143], v154 offset:27648
	ds_read_b64_tr_b16 v[144:145], v154 offset:28416
	ds_read_b64_tr_b16 v[146:147], v154 offset:24640
	ds_read_b64_tr_b16 v[148:149], v154 offset:25408
	ds_read_b64_tr_b16 v[150:151], v154 offset:27712
	ds_read_b64_tr_b16 v[152:153], v154 offset:28480
	s_cbranch_vccnz .LBB0_221
	s_cmp_gt_i32 s5, s47
	s_cselect_b64 s[10:11], -1, 0
	s_cmpk_gt_u32 s5, 0x1fe0
	s_cselect_b64 s[22:23], -1, 0
	s_or_b64 s[26:27], s[10:11], s[22:23]

; #define LAS __attribute__((address_space(3)))
; __device__ __forceinline__ float xmax32(float v) { const auto r = __builtin_amdgcn_permlane32_swap(__float_as_uint(v), __float_as_uint(v), false, false); return __builtin_fmaxf(__uint_as_float(r[0]), __uint_as_float(r[1])); }
; template <int HD, int DV, int HW, int MODE> ...
;     ...
;             const int js = jc + 32 * u;
;             if (js + 31 < iw - HW || js > iw + 31 + HW || js + 31 < 0 || js >= L) continue;
;             f32x16 S;
; #pragma unroll
;             for (int i = 0; i < 16; ++i) S[i] = 0.f;
; #pragma unroll
;             for (int ks = 0; ks < KS; ++ks) { const bf16x8 kf = *(const LAS bf16x8*)(kread + (32 * u) * RSK + 32 * ks); S = __builtin_amdgcn_mfma_f32_32x32x16_bf16(kf, qf[ks], S, 0, 0, 0); }
;             const bool full = (js >= iw + 31 - HW) && (js + 31 <= iw + HW) && js >= 0 && js + 31 < L;
;             if (!full) {
;                 const int qi = iw + ql;
; #pragma unroll
;                 for (int i = 0; i < 16; ++i) { const int j = js + (i & 7) + 8 * hh + 16 * (i >> 3); const int d = qi - j; const bool ok = (d <= HW) && (d >= -HW) && (j >= 0) && (j < L); S[i] = ok ? S[i] : -INFINITY; }
;             }
;             float mt = xmax32(max16(S));
;             if (__any(mt > m + 8.0f)) {
;                 const float mn = fmaxf(m, mt), a = __builtin_amdgcn_exp2f(m - mn); l *= a; m = mn;
; #pragma unroll
;                 for (int t = 0; t < NTV; ++t) O[t] = O[t] * a;
;             }
; #pragma unroll
;             for (int i = 0; i < 16; ++i) S[i] = __builtin_amdgcn_exp2f(S[i] - m);
;             l += sum16(S);
;             const bf16x8 P0 = pack8(S, 0), P1 = pack8(S, 8);
; #pragma unroll
;             for (int t = 0; t < NTV; ++t) {
;                 const LAS unsigned char* vb = vread + (32 * u) * RSV + 64 * t;
;                 const bf16x8 v0 = tr_pair(vb, vb + 4 * RSV), v1 = tr_pair(vb + 16 * RSV, vb + 20 * RSV);
.LBB0_226:
	s_or_b32 s5, s4, 64
	s_or_b32 s2, s4, 0x5f
	s_cmp_lt_i32 s2, s53
	s_cselect_b64 s[10:11], -1, 0
	s_cmp_gt_i32 s5, s52
	s_cselect_b64 s[22:23], -1, 0
	s_or_b64 s[10:11], s[10:11], s[22:23]
	s_cmpk_gt_u32 s2, 0x201e
	s_cselect_b64 s[22:23], -1, 0
	s_or_b64 s[10:11], s[22:23], s[10:11]
	s_and_b64 vcc, exec, s[10:11]
	s_cbranch_vccnz .LBB0_234
	ds_read_b128 v[48:51], v1 offset:9216
	ds_read_b128 v[80:83], v1 offset:9248
	ds_read_b128 v[126:129], v1 offset:9280
	ds_read_b128 v[130:133], v1 offset:9312
	s_cmp_lt_i32 s5, s49
	s_cselect_b64 s[26:27], -1, 0
	s_and_b64 vcc, exec, s[26:27]
	s_waitcnt lgkmcnt(3)
	v_mfma_f32_32x32x16_bf16 v[48:63], v[48:51], v[76:79], 0
	s_waitcnt lgkmcnt(2)
	v_mfma_f32_32x32x16_bf16 v[48:63], v[80:83], v[72:75], v[48:63]
	s_waitcnt lgkmcnt(1)
	v_mfma_f32_32x32x16_bf16 v[48:63], v[126:129], v[68:71], v[48:63]
	s_waitcnt lgkmcnt(0)
	v_mfma_f32_32x32x16_bf16 v[48:63], v[130:133], v[64:67], v[48:63]
	v_add_u32_e32 v154, v103, v105
	ds_read_b64_tr_b16 v[138:139], v154 offset:30720
	ds_read_b64_tr_b16 v[140:141], v154 offset:31488
	ds_read_b64_tr_b16 v[142:143], v154 offset:33792
	ds_read_b64_tr_b16 v[144:145], v154 offset:34560
	ds_read_b64_tr_b16 v[146:147], v154 offset:30784
	ds_read_b64_tr_b16 v[148:149], v154 offset:31552
	ds_read_b64_tr_b16 v[150:151], v154 offset:33856
	ds_read_b64_tr_b16 v[152:153], v154 offset:34624
	s_cbranch_vccnz .LBB0_229
	s_cmp_gt_i32 s5, s47
	s_cselect_b64 s[10:11], -1, 0
	s_cmpk_gt_u32 s5, 0x1fe0
	s_cselect_b64 s[22:23], -1, 0
	s_or_b64 s[26:27], s[10:11], s[22:23]
